# attention softmax: bpermute partner-lane index hoisted out of the tile loop (-6 VALU/tile), useless +0 add dropped
# speedup vs baseline: 1.0090x; 1.0090x over previous
; __device__ __forceinline__ void unpack8(const u32x4 w, float (&f)[8]) { f[0] = bflo(w.x); f[1] = bfhi(w.x); f[2] = bflo(w.y); f[3] = bfhi(w.y); f[4] = bflo(w.z); f[5] = bfhi(w.z); f[6] = bflo(w.w); f[7] = bfhi(w.w); }
; __device__ __forceinline__ u32x4 pack8(const float (&f)[8]) { u32x4 w; w.x = pk_bf16(f[0], f[1]); w.y = pk_bf16(f[2], f[3]); w.z = pk_bf16(f[4], f[5]); w.w = pk_bf16(f[6], f[7]); return w; }
; __device__ __forceinline__ void attn_phase(LAS unsigned char* lds, const bf16* Q, const bf16* KV, const bf16* KPE, const float* rope, bf16* mix, int bid, int G, int tid) {
;     ...
;     for (int round = 0; round * G < AT_UNITS; ++round) {
;         int idx;
;         if (G == 256) { const int i2 = bid >> 1, od = bid & 1;
;             idx = (round == 0) ? bid : (round == 1 ? 256 + (od ? 127 - i2 : 255 - i2) : 512 + (od ? 255 - i2 : 127 - i2)); }
;         else idx = (round & 1) ? (round * G + (G - 1 - bid)) : (round * G + bid);
;         if (idx >= AT_UNITS) continue;
;         int tid_r = tid; asm volatile("" : "+v"(tid_r));
;         const int lane = tid_r & 63, l32 = lane & 31, hh = lane >> 5;
;         const int sr16 = tid_r >> 4, sc16 = tid_r & 15, sr8 = tid_r >> 3, sc8 = tid_r & 7;
;         const int qb = 15 - idx / 48, bh = idx % 48, b = bh / 12, h = bh - b * 12;
;         const int q0 = qb * 256, mrow0 = b * SEQ, ntiles = (qb + 1) * 4;
;         const int qrow = mrow0 + q0 + wid * 32 + l32;
;         bf16x8 qf[12];
;         { const bf16* qp = Q + (size_t)qrow * 2304 + h * 192 + hh * 8; const float* rp = rope + (size_t)qrow * 64;
; #pragma unroll
;           for (int ks = 0; ks < 8; ++ks) { float f[8]; unpack8(*(const u32x4*)(qp + ks * 16), f);
; #pragma unroll
;               for (int e = 0; e < 8; ++e) f[e] *= qs;
;               qf[ks] = __builtin_bit_cast(bf16x8, pack8(f)); if (ks & 1) asm volatile("" ::: "memory"); }
.LBB0_249:
	s_cmpk_gt_i32 s4, 0x2ff
	s_cbranch_scc1 .LBB0_240
	s_mul_hi_i32 s0, s4, 0xd5555555
	s_lshr_b32 s1, s0, 31
	s_ashr_i32 s0, s0, 3
	s_add_i32 s1, s0, s1
	s_mul_hi_i32 s0, s4, 0x2aaaaaab
	s_lshr_b32 s5, s0, 31
	s_lshr_b32 s0, s0, 3
	s_add_i32 s0, s0, s5
	s_mul_i32 s0, s0, 48
	s_sub_i32 s4, s4, s0
	s_mul_i32 s0, s4, 43
	s_sext_i32_i16 s5, s0
	s_lshr_b32 s5, s5, 9
	s_bfe_u32 s0, s0, 0x1000f
	s_add_i32 s5, s5, s0
	s_sext_i32_i16 s0, s5
	s_mul_i32 s7, s0, -12
	s_add_i32 s7, s7, s4
	s_lshl_b32 s4, s1, 8
	s_waitcnt vmcnt(0)
	v_mov_b32_e32 v23, v186
	s_lshl_b32 s34, s0, 12
	s_add_i32 s8, s2, s4
	s_add_i32 s4, s34, s8
	v_and_b32_e32 v22, 31, v23
	v_or_b32_e32 v174, s4, v22
	v_readlane_b32 s4, v255, 1
	v_readlane_b32 s5, v255, 2
	v_bfe_u32 v24, v23, 5, 1
	v_lshlrev_b32_e32 v96, 4, v24
	s_waitcnt lgkmcnt(0)
	v_mov_b64_e32 v[0:1], s[4:5]
	s_movk_i32 s4, 0x1200
	v_mad_i64_i32 v[0:1], s[4:5], v174, s4, v[0:1]
	s_mul_i32 s4, s7, 0xc0
	s_ashr_i32 s5, s4, 31
	v_lshl_add_u64 v[0:1], s[4:5], 1, v[0:1]
	v_lshl_add_u64 v[4:5], v[0:1], 0, v[96:97]
	global_load_dwordx4 v[6:9], v[4:5], off
	global_load_dwordx4 v[10:13], v[4:5], off offset:32
	global_load_dwordx4 v[14:17], v[4:5], off offset:64
	global_load_dwordx4 v[26:29], v[4:5], off offset:96
	global_load_dwordx4 v[30:33], v[4:5], off offset:128
	global_load_dwordx4 v[34:37], v[4:5], off offset:160
	s_mov_b32 s28, 0x3dd53b94
	v_ashrrev_i32_e32 v175, 31, v174
	v_lshlrev_b64 v[18:19], 8, v[174:175]
	global_load_dwordx4 v[38:41], v[4:5], off offset:192
	global_load_dwordx4 v[0:3], v[4:5], off offset:224
	s_lshl_b32 s9, s1, 2
	s_add_i32 s9, s9, 64
	s_ashr_i32 s35, s34, 31
	s_mul_i32 s17, s0, 0x1800000
	v_readlane_b32 s0, v255, 5
	s_mul_hi_i32 s19, s34, 0x1800
	v_readlane_b32 s1, v255, 6
	s_add_u32 s4, s0, s17
	s_addc_u32 s5, s1, s19
	s_lshl_b32 s0, s7, 8
	s_ashr_i32 s1, s0, 31
	v_ashrrev_i32_e32 v25, 4, v23
	s_lshl_b64 s[0:1], s[0:1], 1
	s_movk_i32 s11, 0x1800
	s_add_u32 s14, s4, s0
	s_addc_u32 s15, s5, s1
	s_lshl_b64 s[4:5], s[34:35], 7
	v_readlane_b32 s30, v255, 3
	v_readlane_b32 s31, v255, 4
	s_add_u32 s30, s30, s4
	s_addc_u32 s31, s31, s5
	v_lshlrev_b32_e32 v189, 2, v24
	v_mul_u32_u24_e32 v203, 0x190, v22
	v_or_b32_e32 v206, s8, v22
	v_mov_b32_e32 v184, 0xf149f2ca
	v_mov_b32_e32 v207, 0
	s_waitcnt vmcnt(0) lgkmcnt(0)
	v_lshlrev_b32_e32 v42, 16, v8
	v_and_b32_e32 v43, 0xffff0000, v8
	v_lshlrev_b32_e32 v8, 16, v9
	v_and_b32_e32 v9, 0xffff0000, v9
	v_lshlrev_b32_e32 v44, 16, v10
	v_and_b32_e32 v45, 0xffff0000, v10
	v_lshlrev_b32_e32 v10, 16, v11
	v_and_b32_e32 v11, 0xffff0000, v11
	v_pk_mul_f32 v[8:9], v[8:9], s[28:29] op_sel_hi:[1,0]
	v_lshlrev_b32_e32 v48, 16, v14
	v_and_b32_e32 v49, 0xffff0000, v14
	v_lshlrev_b32_e32 v14, 16, v15
	v_and_b32_e32 v15, 0xffff0000, v15
	v_pk_mul_f32 v[10:11], v[10:11], s[28:29] op_sel_hi:[1,0]
	v_lshlrev_b32_e32 v50, 16, v16
	v_and_b32_e32 v51, 0xffff0000, v16
	v_cvt_pk_bf16_f32 v101, v8, v9
	v_pk_mul_f32 v[8:9], v[14:15], s[28:29] op_sel_hi:[1,0]
	v_lshlrev_b32_e32 v20, 16, v6
	v_and_b32_e32 v21, 0xffff0000, v6
	v_lshlrev_b32_e32 v46, 16, v12
	v_and_b32_e32 v47, 0xffff0000, v12
	v_lshlrev_b32_e32 v12, 16, v13
	v_and_b32_e32 v13, 0xffff0000, v13
	v_cvt_pk_bf16_f32 v103, v10, v11
	v_pk_mul_f32 v[10:11], v[50:51], s[28:29] op_sel_hi:[1,0]
	v_cvt_pk_bf16_f32 v107, v8, v9
	v_lshlrev_b32_e32 v8, 16, v27
	v_and_b32_e32 v9, 0xffff0000, v27
	v_pk_mul_f32 v[20:21], v[20:21], s[28:29] op_sel_hi:[1,0]
	v_pk_mul_f32 v[12:13], v[12:13], s[28:29] op_sel_hi:[1,0]
	v_lshlrev_b32_e32 v16, 16, v17
	v_and_b32_e32 v17, 0xffff0000, v17
	v_lshlrev_b32_e32 v52, 16, v26
	v_and_b32_e32 v53, 0xffff0000, v26
	v_cvt_pk_bf16_f32 v108, v10, v11
	v_pk_mul_f32 v[26:27], v[8:9], s[28:29] op_sel_hi:[1,0]
	v_lshl_add_u64 v[8:9], s[56:57], 0, v[18:19]
	v_lshlrev_b32_e32 v10, 6, v24
	v_mov_b32_e32 v11, v97
	v_cvt_pk_bf16_f32 v98, v20, v21
	v_cvt_pk_bf16_f32 v105, v12, v13
	v_pk_mul_f32 v[12:13], v[16:17], s[28:29] op_sel_hi:[1,0]
	v_lshl_add_u64 v[20:21], v[8:9], 0, v[10:11]
	v_cvt_pk_bf16_f32 v109, v12, v13
	global_load_dwordx4 v[16:19], v[20:21], off
	global_load_dwordx4 v[8:11], v[4:5], off offset:256
	global_load_dwordx4 v[12:15], v[4:5], off offset:320
	v_lshlrev_b32_e32 v6, 16, v7
	v_and_b32_e32 v7, 0xffff0000, v7
	v_pk_mul_f32 v[6:7], v[6:7], s[28:29] op_sel_hi:[1,0]
	v_pk_mul_f32 v[42:43], v[42:43], s[28:29] op_sel_hi:[1,0]
	v_cvt_pk_bf16_f32 v99, v6, v7
	v_pk_mul_f32 v[6:7], v[48:49], s[28:29] op_sel_hi:[1,0]
	v_cvt_pk_bf16_f32 v100, v42, v43
	v_cvt_pk_bf16_f32 v106, v6, v7
	v_pk_mul_f32 v[6:7], v[52:53], s[28:29] op_sel_hi:[1,0]
	v_lshlrev_b32_e32 v42, 16, v28
	v_and_b32_e32 v43, 0xffff0000, v28
	v_cvt_pk_bf16_f32 v111, v26, v27
	v_lshlrev_b32_e32 v26, 16, v31
	v_and_b32_e32 v27, 0xffff0000, v31
	v_pk_mul_f32 v[42:43], v[42:43], s[28:29] op_sel_hi:[1,0]
	v_lshlrev_b32_e32 v28, 16, v29
	v_and_b32_e32 v29, 0xffff0000, v29
	v_cvt_pk_bf16_f32 v110, v6, v7
	v_lshlrev_b32_e32 v6, 16, v30
	v_and_b32_e32 v7, 0xffff0000, v30
	v_pk_mul_f32 v[30:31], v[26:27], s[28:29] op_sel_hi:[1,0]
	v_lshlrev_b32_e32 v26, 16, v32
	v_and_b32_e32 v27, 0xffff0000, v32
	v_pk_mul_f32 v[28:29], v[28:29], s[28:29] op_sel_hi:[1,0]
	v_cvt_pk_bf16_f32 v112, v42, v43
	v_pk_mul_f32 v[6:7], v[6:7], s[28:29] op_sel_hi:[1,0]
	v_pk_mul_f32 v[42:43], v[26:27], s[28:29] op_sel_hi:[1,0]
	v_lshlrev_b32_e32 v26, 16, v33
	v_and_b32_e32 v27, 0xffff0000, v33
	v_cvt_pk_bf16_f32 v113, v28, v29
	v_pk_mul_f32 v[32:33], v[26:27], s[28:29] op_sel_hi:[1,0]
	global_load_dwordx4 v[26:29], v[20:21], off offset:16
	v_cvt_pk_bf16_f32 v114, v6, v7
	v_cvt_pk_bf16_f32 v115, v30, v31
	v_lshlrev_b32_e32 v6, 16, v34
	v_and_b32_e32 v7, 0xffff0000, v34
; __device__ __forceinline__ void unpack8(const u32x4 w, float (&f)[8]) { f[0] = bflo(w.x); f[1] = bfhi(w.x); f[2] = bflo(w.y); f[3] = bfhi(w.y); f[4] = bflo(w.z); f[5] = bfhi(w.z); f[6] = bflo(w.w); f[7] = bfhi(w.w); }
; __device__ __forceinline__ u32x4 pack8(const float (&f)[8]) { u32x4 w; w.x = pk_bf16(f[0], f[1]); w.y = pk_bf16(f[2], f[3]); w.z = pk_bf16(f[4], f[5]); w.w = pk_bf16(f[6], f[7]); return w; }
; __device__ __forceinline__ void attn_phase(LAS unsigned char* lds, const bf16* Q, const bf16* KV, const bf16* KPE, const float* rope, bf16* mix, int bid, int G, int tid) {
;     ...
;           for (int ks = 0; ks < 8; ++ks) { float f[8]; unpack8(*(const u32x4*)(qp + ks * 16), f);
; #pragma unroll
;               for (int e = 0; e < 8; ++e) f[e] *= qs;
;               qf[ks] = __builtin_bit_cast(bf16x8, pack8(f)); if (ks & 1) asm volatile("" ::: "memory"); }
; #pragma unroll
;           for (int ks = 8; ks < 10; ++ks) { float f1[8], f2[8], o1[8], o2[8]; unpack8(*(const u32x4*)(qp + ks * 16), f1); unpack8(*(const u32x4*)(qp + (ks + 2) * 16), f2);
; #pragma unroll
;               for (int e = 0; e < 8; ++e) { const int i = (ks - 8) * 16 + hh * 8 + e; const float cs = rp[2 * i], sn = rp[2 * i + 1];
;                   o1[e] = (f1[e] * cs - f2[e] * sn) * qs; o2[e] = (f1[e] * sn + f2[e] * cs) * qs; }
;               qf[ks] = __builtin_bit_cast(bf16x8, pack8(o1)); qf[ks + 2] = __builtin_bit_cast(bf16x8, pack8(o2)); asm volatile("" ::: "memory"); } }
	v_lshlrev_b32_e32 v30, 16, v35
	v_and_b32_e32 v31, 0xffff0000, v35
	v_lshlrev_b32_e32 v34, 16, v37
	v_and_b32_e32 v35, 0xffff0000, v37
	v_cvt_pk_bf16_f32 v117, v32, v33
	v_pk_mul_f32 v[6:7], v[6:7], s[28:29] op_sel_hi:[1,0]
	v_lshlrev_b32_e32 v32, 16, v36
	v_and_b32_e32 v33, 0xffff0000, v36
	v_pk_mul_f32 v[34:35], v[34:35], s[28:29] op_sel_hi:[1,0]
	v_pk_mul_f32 v[30:31], v[30:31], s[28:29] op_sel_hi:[1,0]
	v_pk_mul_f32 v[32:33], v[32:33], s[28:29] op_sel_hi:[1,0]
	v_cvt_pk_bf16_f32 v118, v6, v7
	v_cvt_pk_bf16_f32 v121, v34, v35
	v_lshlrev_b32_e32 v6, 16, v38
	v_and_b32_e32 v7, 0xffff0000, v38
	v_lshlrev_b32_e32 v34, 16, v39
	v_and_b32_e32 v35, 0xffff0000, v39
	v_lshlrev_b32_e32 v38, 16, v41
	v_and_b32_e32 v39, 0xffff0000, v41
	v_cvt_pk_bf16_f32 v119, v30, v31
	v_cvt_pk_bf16_f32 v120, v32, v33
	global_load_dwordx4 v[30:33], v[20:21], off offset:32
	v_pk_mul_f32 v[38:39], v[38:39], s[28:29] op_sel_hi:[1,0]
	v_pk_mul_f32 v[6:7], v[6:7], s[28:29] op_sel_hi:[1,0]
	v_lshlrev_b32_e32 v36, 16, v40
	v_and_b32_e32 v37, 0xffff0000, v40
	v_cvt_pk_bf16_f32 v125, v38, v39
	v_lshlrev_b32_e32 v38, 16, v2
	v_and_b32_e32 v39, 0xffff0000, v2
	v_lshlrev_b32_e32 v2, 16, v3
	v_and_b32_e32 v3, 0xffff0000, v3
	v_pk_mul_f32 v[34:35], v[34:35], s[28:29] op_sel_hi:[1,0]
	v_pk_mul_f32 v[36:37], v[36:37], s[28:29] op_sel_hi:[1,0]
	v_cvt_pk_bf16_f32 v122, v6, v7
	v_lshlrev_b32_e32 v6, 16, v0
	v_and_b32_e32 v7, 0xffff0000, v0
	v_lshlrev_b32_e32 v0, 16, v1
	v_and_b32_e32 v1, 0xffff0000, v1
	v_pk_mul_f32 v[2:3], v[2:3], s[28:29] op_sel_hi:[1,0]
	v_pk_mul_f32 v[44:45], v[44:45], s[28:29] op_sel_hi:[1,0]
	v_cvt_pk_bf16_f32 v116, v42, v43
	v_cvt_pk_bf16_f32 v123, v34, v35
	v_cvt_pk_bf16_f32 v124, v36, v37
	global_load_dwordx4 v[34:37], v[20:21], off offset:48
	v_pk_mul_f32 v[0:1], v[0:1], s[28:29] op_sel_hi:[1,0]
	v_cvt_pk_bf16_f32 v129, v2, v3
	s_waitcnt vmcnt(0) lgkmcnt(0)
	v_lshlrev_b32_e32 v42, 16, v12
	v_and_b32_e32 v43, 0xffff0000, v8
	v_mov_b32_e32 v2, v16
	v_mov_b32_e32 v3, v19
	v_cvt_pk_bf16_f32 v102, v44, v45
	v_cvt_pk_bf16_f32 v127, v0, v1
	v_mov_b32_e32 v0, v17
	v_mov_b32_e32 v1, v18
	v_lshlrev_b32_e32 v44, 16, v8
	v_and_b32_e32 v45, 0xffff0000, v12
	v_pk_mul_f32 v[2:3], v[2:3], v[42:43]
	v_pk_mul_f32 v[46:47], v[46:47], s[28:29] op_sel_hi:[1,0]
	v_pk_mul_f32 v[6:7], v[6:7], s[28:29] op_sel_hi:[1,0]
	v_pk_mul_f32 v[38:39], v[38:39], s[28:29] op_sel_hi:[1,0]
	v_pk_fma_f32 v[0:1], v[0:1], v[44:45], v[2:3]
	v_cvt_pk_bf16_f32 v104, v46, v47
	v_cvt_pk_bf16_f32 v126, v6, v7
	v_cvt_pk_bf16_f32 v128, v38, v39
	v_pk_mul_f32 v[46:47], v[0:1], s[28:29] op_sel_hi:[1,0]
	global_load_dwordx4 v[38:41], v[20:21], off offset:128
	global_load_dwordx4 v[0:3], v[4:5], off offset:288
	s_nop 0
	global_load_dwordx4 v[4:7], v[4:5], off offset:352
	v_mov_b32_e32 v49, v18
	v_mov_b32_e32 v51, v43
	v_mov_b32_e32 v18, v17
	v_mov_b32_e32 v43, v45
	v_mov_b32_e32 v48, v16
	v_mov_b32_e32 v50, v44
	v_pk_mul_f32 v[16:17], v[18:19], v[42:43]
	v_lshlrev_b32_e32 v44, 16, v13
	v_pk_fma_f32 v[16:17], v[48:49], v[50:51], v[16:17] neg_lo:[0,0,1] neg_hi:[0,0,1]
	v_and_b32_e32 v45, 0xffff0000, v9
	v_lshlrev_b32_e32 v8, 16, v9
	v_and_b32_e32 v9, 0xffff0000, v13
	v_mov_b32_e32 v12, v26
	v_mov_b32_e32 v13, v29
	v_pk_mul_f32 v[42:43], v[16:17], s[28:29] op_sel_hi:[1,0]
	v_mov_b32_e32 v16, v27
	v_mov_b32_e32 v17, v28
	v_pk_mul_f32 v[12:13], v[12:13], v[44:45]
	v_mov_b32_e32 v49, v28
	v_mov_b32_e32 v51, v45
	v_mov_b32_e32 v28, v27
	v_mov_b32_e32 v45, v9
	v_pk_fma_f32 v[12:13], v[16:17], v[8:9], v[12:13]
	v_mov_b32_e32 v48, v26
	v_mov_b32_e32 v50, v8
	v_pk_mul_f32 v[8:9], v[28:29], v[44:45]
	v_lshlrev_b32_e32 v28, 16, v14
	v_pk_fma_f32 v[8:9], v[48:49], v[50:51], v[8:9] neg_lo:[0,0,1] neg_hi:[0,0,1]
	v_and_b32_e32 v29, 0xffff0000, v10
	v_lshlrev_b32_e32 v44, 16, v10
	v_and_b32_e32 v45, 0xffff0000, v14
	v_mov_b32_e32 v51, v29
	v_mov_b32_e32 v50, v44
	v_lshlrev_b32_e32 v10, 16, v11
	v_mov_b32_e32 v48, v30
	v_mov_b32_e32 v49, v33
	v_mov_b32_e32 v26, v31
	v_mov_b32_e32 v27, v32
	v_pk_mul_f32 v[48:49], v[48:49], v[28:29]
	v_mov_b32_e32 v29, v45
	v_pk_fma_f32 v[26:27], v[26:27], v[44:45], v[48:49]
	v_mov_b32_e32 v49, v32
	v_mov_b32_e32 v32, v31
	v_mov_b32_e32 v48, v30
	v_pk_mul_f32 v[28:29], v[32:33], v[28:29]
	v_lshlrev_b32_e32 v32, 16, v15
	v_and_b32_e32 v33, 0xffff0000, v11
	v_and_b32_e32 v11, 0xffff0000, v15
	v_pk_fma_f32 v[28:29], v[48:49], v[50:51], v[28:29] neg_lo:[0,0,1] neg_hi:[0,0,1]
	v_mov_b32_e32 v45, v33
	v_pk_mul_f32 v[26:27], v[26:27], s[28:29] op_sel_hi:[1,0]
	v_pk_mul_f32 v[28:29], v[28:29], s[28:29] op_sel_hi:[1,0]
	v_mov_b32_e32 v44, v10
	v_pk_mul_f32 v[12:13], v[12:13], s[28:29] op_sel_hi:[1,0]
	global_load_dwordx4 v[16:19], v[20:21], off offset:144
	v_cvt_pk_bf16_f32 v132, v28, v29
	v_mov_b32_e32 v14, v34
	v_mov_b32_e32 v15, v37
	v_mov_b32_e32 v30, v35
	v_mov_b32_e32 v31, v36
	v_pk_mul_f32 v[14:15], v[14:15], v[32:33]
	v_mov_b32_e32 v36, v35
	v_mov_b32_e32 v33, v11
	v_pk_fma_f32 v[14:15], v[30:31], v[10:11], v[14:15]
	v_mov_b32_e32 v30, v34
	v_pk_mul_f32 v[10:11], v[36:37], v[32:33]
	v_pk_mul_f32 v[14:15], v[14:15], s[28:29] op_sel_hi:[1,0]
	v_pk_fma_f32 v[10:11], v[30:31], v[44:45], v[10:11] neg_lo:[0,0,1] neg_hi:[0,0,1]
	v_cvt_pk_bf16_f32 v136, v26, v27
	v_pk_mul_f32 v[8:9], v[8:9], s[28:29] op_sel_hi:[1,0]
	v_pk_mul_f32 v[10:11], v[10:11], s[28:29] op_sel_hi:[1,0]
	v_cvt_pk_bf16_f32 v135, v12, v13
	v_cvt_pk_bf16_f32 v137, v14, v15
	v_cvt_pk_bf16_f32 v131, v8, v9
	v_cvt_pk_bf16_f32 v133, v10, v11
	global_load_dwordx4 v[8:11], v[20:21], off offset:160
	v_ashrrev_i32_e32 v52, 3, v23
	s_waitcnt vmcnt(0) lgkmcnt(0)
; __device__ __forceinline__ void unpack8(const u32x4 w, float (&f)[8]) { f[0] = bflo(w.x); f[1] = bfhi(w.x); f[2] = bflo(w.y); f[3] = bfhi(w.y); f[4] = bflo(w.z); f[5] = bfhi(w.z); f[6] = bflo(w.w); f[7] = bfhi(w.w); }
; __device__ __forceinline__ u32x4 pack8(const float (&f)[8]) { u32x4 w; w.x = pk_bf16(f[0], f[1]); w.y = pk_bf16(f[2], f[3]); w.z = pk_bf16(f[4], f[5]); w.w = pk_bf16(f[6], f[7]); return w; }
; __device__ __forceinline__ void attn_phase(LAS unsigned char* lds, const bf16* Q, const bf16* KV, const bf16* KPE, const float* rope, bf16* mix, int bid, int G, int tid) {
;     ...
;         { const bf16* qp = Q + (size_t)qrow * 2304 + h * 192 + hh * 8; const float* rp = rope + (size_t)qrow * 64;
; #pragma unroll
;           for (int ks = 0; ks < 8; ++ks) { float f[8]; unpack8(*(const u32x4*)(qp + ks * 16), f);
; #pragma unroll
;               for (int e = 0; e < 8; ++e) f[e] *= qs;
;               qf[ks] = __builtin_bit_cast(bf16x8, pack8(f)); if (ks & 1) asm volatile("" ::: "memory"); }
; #pragma unroll
;           for (int ks = 8; ks < 10; ++ks) { float f1[8], f2[8], o1[8], o2[8]; unpack8(*(const u32x4*)(qp + ks * 16), f1); unpack8(*(const u32x4*)(qp + (ks + 2) * 16), f2);
; #pragma unroll
;               for (int e = 0; e < 8; ++e) { const int i = (ks - 8) * 16 + hh * 8 + e; const float cs = rp[2 * i], sn = rp[2 * i + 1];
;                   o1[e] = (f1[e] * cs - f2[e] * sn) * qs; o2[e] = (f1[e] * sn + f2[e] * cs) * qs; }
;               qf[ks] = __builtin_bit_cast(bf16x8, pack8(o1)); qf[ks + 2] = __builtin_bit_cast(bf16x8, pack8(o2)); asm volatile("" ::: "memory"); } }
;         f32x16 O[4];
; #pragma unroll
;         for (int i = 0; i < 4; ++i)
; #pragma unroll
;             for (int e = 0; e < 16; ++e) O[i][e] = 0.f;
;         float mrun = -1e30f, lrun = 0.f;
;         u32x4 sk[3], sv[2];
;         const char* kvb = (const char*)(KV + (size_t)mrow0 * 3072 + h * 256); const char* kpb = (const char*)(KPE + (size_t)mrow0 * 64);
;         const unsigned kvo = (unsigned)(sr16 * 3072 + sc16 * 8) * 2u, kpo = (unsigned)(sr8 * 64 + sc8 * 8) * 2u;
;     ...
;         AT_ISSUE(0); AT_COMMIT(lds);
;         __syncthreads();
;     ...
;                 mx = fmaxf(mx, __shfl_xor(mx, 32));
	v_mov_b32_e32 v28, v38
	v_and_b32_e32 v27, 0xffff0000, v0
	v_lshlrev_b32_e32 v26, 16, v4
	v_mov_b32_e32 v29, v41
	v_mov_b32_e32 v12, v39
	v_mov_b32_e32 v13, v40
	v_lshlrev_b32_e32 v14, 16, v0
	v_and_b32_e32 v15, 0xffff0000, v4
	v_pk_mul_f32 v[28:29], v[28:29], v[26:27]
	v_mov_b32_e32 v31, v40
	v_pk_fma_f32 v[12:13], v[12:13], v[14:15], v[28:29]
	v_mov_b32_e32 v33, v27
	v_mov_b32_e32 v40, v39
	v_mov_b32_e32 v27, v15
	v_lshlrev_b32_e32 v0, 4, v23
	v_pk_mul_f32 v[28:29], v[12:13], s[28:29] op_sel_hi:[1,0]
	v_mov_b32_e32 v30, v38
	v_mov_b32_e32 v32, v14
	global_load_dwordx4 v[12:15], v[20:21], off offset:176
	v_pk_mul_f32 v[20:21], v[40:41], v[26:27]
	v_and_b32_e32 v187, 0xf0, v0
	v_mul_lo_u32 v4, v25, s11
	v_pk_fma_f32 v[20:21], v[30:31], v[32:33], v[20:21] neg_lo:[0,0,1] neg_hi:[0,0,1]
	v_or_b32_e32 v30, v187, v4
	v_mov_b32_e32 v31, v97
	v_lshl_add_u64 v[34:35], s[14:15], 0, v[30:31]
	v_and_b32_e32 v188, 0x70, v0
	global_load_dwordx4 v[138:141], v[34:35], off
	global_load_dwordx4 v[146:149], v[34:35], off offset:256
	v_add_u32_e32 v36, 0x30000, v30
	v_mov_b32_e32 v37, v97
	v_add_u32_e32 v34, 0x30100, v30
	v_mov_b32_e32 v35, v97
	v_lshl_or_b32 v32, v52, 7, v188
	v_lshl_add_u64 v[38:39], s[14:15], 0, v[36:37]
	v_mov_b32_e32 v33, v97
	v_lshl_add_u64 v[40:41], s[14:15], 0, v[34:35]
	global_load_dwordx4 v[142:145], v[38:39], off
	global_load_dwordx4 v[154:157], v[40:41], off
	v_lshl_add_u64 v[38:39], s[30:31], 0, v[32:33]
	global_load_dwordx4 v[150:153], v[38:39], off
	v_lshlrev_b32_e32 v38, 16, v5
	v_and_b32_e32 v39, 0xffff0000, v1
	v_lshlrev_b32_e32 v0, 16, v1
	v_and_b32_e32 v1, 0xffff0000, v5
	v_mov_b32_e32 v41, v39
	v_mov_b32_e32 v40, v0
	s_movk_i32 s11, 0x190
	v_mul_lo_u32 v190, v25, s11
	v_mul_lo_u32 v192, v52, s11
	s_movk_i32 s11, 0x140
	v_mul_lo_u32 v193, v25, s11
	s_movk_i32 s11, 0xffb0
	v_pk_mul_f32 v[20:21], v[20:21], s[28:29] op_sel_hi:[1,0]
	v_cvt_pk_bf16_f32 v130, v42, v43
	v_cvt_pk_bf16_f32 v134, v46, v47
	v_mov_b32_e32 v4, v16
	v_mov_b32_e32 v5, v19
	v_mov_b32_e32 v26, v17
	v_mov_b32_e32 v27, v18
	v_pk_mul_f32 v[4:5], v[4:5], v[38:39]
	v_mov_b32_e32 v18, v17
	v_mov_b32_e32 v39, v1
	v_pk_fma_f32 v[4:5], v[26:27], v[0:1], v[4:5]
	v_mov_b32_e32 v26, v16
	v_pk_mul_f32 v[0:1], v[18:19], v[38:39]
	v_lshlrev_b32_e32 v18, 16, v6
	v_and_b32_e32 v19, 0xffff0000, v2
	v_pk_fma_f32 v[0:1], v[26:27], v[40:41], v[0:1] neg_lo:[0,0,1] neg_hi:[0,0,1]
	v_lshlrev_b32_e32 v26, 16, v2
	v_and_b32_e32 v27, 0xffff0000, v6
	v_mov_b32_e32 v41, v19
	v_lshlrev_b32_e32 v2, 16, v3
	v_pk_mul_f32 v[0:1], v[0:1], s[28:29] op_sel_hi:[1,0]
	v_mov_b32_e32 v40, v26
	v_cvt_pk_bf16_f32 v159, v0, v1
	v_add3_u32 v0, 0, v190, v187
	v_mov_b32_e32 v38, v8
	v_mov_b32_e32 v39, v11
	v_mov_b32_e32 v16, v9
	v_mov_b32_e32 v17, v10
	v_pk_mul_f32 v[38:39], v[38:39], v[18:19]
	v_mov_b32_e32 v19, v27
	v_pk_fma_f32 v[16:17], v[16:17], v[26:27], v[38:39]
	v_mov_b32_e32 v39, v10
	v_mov_b32_e32 v10, v9
	v_mov_b32_e32 v38, v8
	v_pk_mul_f32 v[8:9], v[10:11], v[18:19]
	v_lshlrev_b32_e32 v18, 16, v7
	v_and_b32_e32 v19, 0xffff0000, v3
	v_and_b32_e32 v3, 0xffff0000, v7
	v_mov_b32_e32 v27, v19
	v_mov_b32_e32 v26, v2
	v_add3_u32 v1, 0, v192, v188
	v_pk_fma_f32 v[8:9], v[38:39], v[40:41], v[8:9] neg_lo:[0,0,1] neg_hi:[0,0,1]
	v_pk_mul_f32 v[4:5], v[4:5], s[28:29] op_sel_hi:[1,0]
	v_pk_mul_f32 v[16:17], v[16:17], s[28:29] op_sel_hi:[1,0]
	s_waitcnt vmcnt(0) lgkmcnt(0)
	v_mov_b32_e32 v6, v12
	v_mov_b32_e32 v7, v15
	v_mov_b32_e32 v10, v13
	v_mov_b32_e32 v11, v14
	v_pk_mul_f32 v[6:7], v[6:7], v[18:19]
	v_mov_b32_e32 v14, v13
	v_mov_b32_e32 v19, v3
	v_pk_fma_f32 v[6:7], v[10:11], v[2:3], v[6:7]
	v_mov_b32_e32 v10, v12
	v_pk_mul_f32 v[2:3], v[14:15], v[18:19]
	ds_write_b128 v0, v[138:141]
	v_pk_fma_f32 v[2:3], v[10:11], v[26:27], v[2:3] neg_lo:[0,0,1] neg_hi:[0,0,1]
	v_pk_mul_f32 v[8:9], v[8:9], s[28:29] op_sel_hi:[1,0]
	v_pk_mul_f32 v[2:3], v[2:3], s[28:29] op_sel_hi:[1,0]
	v_pk_mul_f32 v[6:7], v[6:7], s[28:29] op_sel_hi:[1,0]
	v_cvt_pk_bf16_f32 v161, v2, v3
	v_mov_b32_e32 v14, v97
	v_mov_b32_e32 v15, v97
	v_cvt_pk_bf16_f32 v158, v20, v21
	v_cvt_pk_bf16_f32 v160, v8, v9
	ds_write_b128 v0, v[142:145] offset:12800
	v_cvt_pk_bf16_f32 v162, v28, v29
	v_cvt_pk_bf16_f32 v163, v4, v5
	ds_write_b128 v1, v[150:153] offset:256
	v_mul_lo_u32 v1, v25, s11
	s_movk_i32 s11, 0x3200
	v_add_u32_e32 v2, v0, v1
	v_add3_u32 v0, v0, s11, v1
	s_or_b32 s11, s8, 31
	s_add_u32 s4, s4, 0x26a02000
	s_addc_u32 s5, s5, 0
	ds_write_b128 v0, v[154:157] offset:23040
	v_lshrrev_b32_e32 v0, 2, v23
	s_add_u32 s0, s17, s0
	v_and_or_b32 v0, v0, 3, v189
	s_addc_u32 s1, s19, s1
	v_mul_u32_u24_e32 v204, 0x140, v0
	v_and_b32_e32 v0, 16, v23
	v_lshlrev_b32_e32 v1, 2, v23
	v_lshl_add_u64 v[176:177], s[4:5], 0, v[32:33]
	s_add_u32 s4, s0, 0x27660000
	v_and_or_b32 v0, v1, 12, v0
	s_addc_u32 s5, s1, 0
	v_cvt_pk_bf16_f32 v164, v16, v17
	v_cvt_pk_bf16_f32 v165, v6, v7
	ds_write_b128 v2, v[146:149] offset:25600
	v_lshlrev_b32_e32 v205, 1, v0
	v_lshl_add_u64 v[178:179], s[4:5], 0, v[34:35]
	v_lshl_add_u64 v[180:181], s[4:5], 0, v[36:37]
	v_lshl_add_u64 v[182:183], s[0:1], 0, v[30:31]
	v_mov_b32_e32 v0, v97
	v_mov_b32_e32 v1, v97
	v_mov_b32_e32 v2, v97
	v_mov_b32_e32 v3, v97
	v_mov_b32_e32 v4, v97
	v_mov_b32_e32 v5, v97
	v_mov_b32_e32 v6, v97
	v_mov_b32_e32 v7, v97
	v_mov_b32_e32 v8, v97
	v_mov_b32_e32 v9, v97
	v_mov_b32_e32 v10, v97
	v_mov_b32_e32 v11, v97
	v_mov_b32_e32 v12, v97
	v_mov_b32_e32 v13, v97
	v_mov_b64_e32 v[30:31], v[14:15]
	v_mov_b64_e32 v[46:47], v[14:15]
	v_mov_b64_e32 v[62:63], v[14:15]
	v_add_u32_e32 v191, 0x3200, v190
	v_add_u32_e32 v202, 0x2800, v193
	s_mov_b32 s4, 0
	s_mov_b32 s0, 63
	v_mov_b64_e32 v[28:29], v[12:13]
	v_mov_b64_e32 v[26:27], v[10:11]
	v_mov_b64_e32 v[24:25], v[8:9]
	v_mov_b64_e32 v[22:23], v[6:7]
	v_mov_b64_e32 v[20:21], v[4:5]
	v_mov_b64_e32 v[18:19], v[2:3]
	v_mov_b64_e32 v[16:17], v[0:1]
	v_mov_b64_e32 v[44:45], v[12:13]
	v_mov_b64_e32 v[42:43], v[10:11]
	v_mov_b64_e32 v[40:41], v[8:9]
	v_mov_b64_e32 v[38:39], v[6:7]
	v_mov_b64_e32 v[36:37], v[4:5]
	v_mov_b64_e32 v[34:35], v[2:3]
	v_mov_b64_e32 v[32:33], v[0:1]
	v_mov_b64_e32 v[60:61], v[12:13]
	v_mov_b64_e32 v[58:59], v[10:11]
	v_mov_b64_e32 v[56:57], v[8:9]
	v_mov_b64_e32 v[54:55], v[6:7]
	v_mov_b64_e32 v[52:53], v[4:5]
	v_mov_b64_e32 v[50:51], v[2:3]
	v_mov_b64_e32 v[48:49], v[0:1]
	s_waitcnt lgkmcnt(0)
	s_barrier
	v_and_b32_e32 v251, 64, v220
	v_xor_b32_e32 v250, 32, v220
	v_add_u32_e32 v251, 64, v251
	v_cmp_lt_i32_e32 vcc, v250, v251
	s_nop 1
	v_cndmask_b32_e32 v250, v220, v250, vcc
	v_lshlrev_b32_e32 v250, 2, v250

; __device__ __forceinline__ void attn_phase(LAS unsigned char* lds, const bf16* Q, const bf16* KV, const bf16* KPE, const float* rope, bf16* mix, int bid, int G, int tid) {
;     ...
;                 float mx = fmaxf(S0[0], S1[0]);
; #pragma unroll
;                 for (int e = 1; e < 16; ++e) mx = fmaxf(mx, fmaxf(S0[e], S1[e]));
;                 mx = fmaxf(mx, __shfl_xor(mx, 32));
;                 const float mnew = (mx > mrun + 6.0f) ? mx : mrun;
;                 const float alpha = __builtin_amdgcn_exp2f(mrun - mnew); mrun = mnew;
;                 float rs = 0.f;
; #pragma unroll
;                 for (int e = 0; e < 16; ++e) { S0[e] = __builtin_amdgcn_exp2f(S0[e] - mnew); S1[e] = __builtin_amdgcn_exp2f(S1[e] - mnew); rs += S0[e] + S1[e]; }
;                 lrun = lrun * alpha + rs;
;                 if (__builtin_amdgcn_ballot_w64(alpha != 1.0f) != 0ull) {
; #pragma unroll
;                     for (int i = 0; i < 4; ++i)
; #pragma unroll
;                         for (int e = 0; e < 16; ++e) O[i][e] *= alpha; }
.LBB0_256:
	s_nop 9
	v_max3_f32 v209, v64, v65, v66
	v_max3_f32 v210, v67, v68, v69
	v_max3_f32 v211, v70, v71, v72
	v_max3_f32 v212, v73, v74, v75
	v_max3_f32 v209, v209, v76, v77
	v_max3_f32 v210, v210, v78, v79
	v_max3_f32 v211, v211, v80, v81
	v_max3_f32 v212, v212, v82, v83
	v_max3_f32 v209, v209, v84, v85
	v_max3_f32 v210, v210, v86, v87
	v_max3_f32 v211, v211, v88, v89
	v_max3_f32 v212, v212, v90, v91
	v_max3_f32 v209, v209, v92, v93
	v_max3_f32 v210, v210, v94, v95
	v_max3_f32 v209, v209, v210, v211
	v_max_f32_e32 v209, v209, v212
	ds_bpermute_b32 v210, v250, v209
	s_waitcnt lgkmcnt(0)
	v_max_f32_e32 v210, v210, v210
	v_max_f32_e32 v209, v209, v210
	v_add_f32_e32 v210, 0x40c00000, v184
	v_cmp_gt_f32_e32 vcc, v209, v210
	s_nop 1
	v_cndmask_b32_e32 v209, v184, v209, vcc
	v_sub_f32_e32 v184, v184, v209
	v_exp_f32_e32 v184, v184
	s_nop 0
	v_cmp_neq_f32_e32 vcc, 1.0, v184
	s_cbranch_vccz .LBB0_258
	v_pk_mul_f32 v[62:63], v[62:63], v[184:185] op_sel_hi:[1,0]
	v_pk_mul_f32 v[60:61], v[60:61], v[184:185] op_sel_hi:[1,0]
	v_pk_mul_f32 v[58:59], v[58:59], v[184:185] op_sel_hi:[1,0]
	v_pk_mul_f32 v[56:57], v[56:57], v[184:185] op_sel_hi:[1,0]
	v_pk_mul_f32 v[54:55], v[54:55], v[184:185] op_sel_hi:[1,0]
	v_pk_mul_f32 v[52:53], v[52:53], v[184:185] op_sel_hi:[1,0]
	v_pk_mul_f32 v[50:51], v[50:51], v[184:185] op_sel_hi:[1,0]
	v_pk_mul_f32 v[48:49], v[48:49], v[184:185] op_sel_hi:[1,0]
	v_pk_mul_f32 v[46:47], v[46:47], v[184:185] op_sel_hi:[1,0]
	v_pk_mul_f32 v[44:45], v[44:45], v[184:185] op_sel_hi:[1,0]
	v_pk_mul_f32 v[42:43], v[42:43], v[184:185] op_sel_hi:[1,0]
	v_pk_mul_f32 v[40:41], v[40:41], v[184:185] op_sel_hi:[1,0]
	v_pk_mul_f32 v[38:39], v[38:39], v[184:185] op_sel_hi:[1,0]
	v_pk_mul_f32 v[36:37], v[36:37], v[184:185] op_sel_hi:[1,0]
	v_pk_mul_f32 v[34:35], v[34:35], v[184:185] op_sel_hi:[1,0]
	v_pk_mul_f32 v[32:33], v[32:33], v[184:185] op_sel_hi:[1,0]
	v_pk_mul_f32 v[30:31], v[30:31], v[184:185] op_sel_hi:[1,0]
	v_pk_mul_f32 v[28:29], v[28:29], v[184:185] op_sel_hi:[1,0]
	v_pk_mul_f32 v[26:27], v[26:27], v[184:185] op_sel_hi:[1,0]
	v_pk_mul_f32 v[24:25], v[24:25], v[184:185] op_sel_hi:[1,0]
	v_pk_mul_f32 v[22:23], v[22:23], v[184:185] op_sel_hi:[1,0]
	v_pk_mul_f32 v[20:21], v[20:21], v[184:185] op_sel_hi:[1,0]
	v_pk_mul_f32 v[18:19], v[18:19], v[184:185] op_sel_hi:[1,0]
	v_pk_mul_f32 v[16:17], v[16:17], v[184:185] op_sel_hi:[1,0]
	v_pk_mul_f32 v[14:15], v[14:15], v[184:185] op_sel_hi:[1,0]
	v_pk_mul_f32 v[12:13], v[12:13], v[184:185] op_sel_hi:[1,0]
	v_pk_mul_f32 v[10:11], v[10:11], v[184:185] op_sel_hi:[1,0]
	v_pk_mul_f32 v[8:9], v[8:9], v[184:185] op_sel_hi:[1,0]
	v_pk_mul_f32 v[6:7], v[6:7], v[184:185] op_sel_hi:[1,0]
	v_pk_mul_f32 v[4:5], v[4:5], v[184:185] op_sel_hi:[1,0]
	v_pk_mul_f32 v[2:3], v[2:3], v[184:185] op_sel_hi:[1,0]
	v_pk_mul_f32 v[0:1], v[0:1], v[184:185] op_sel_hi:[1,0]
; __device__ __forceinline__ u32x4 pack8(const float (&f)[8]) { u32x4 w; w.x = pk_bf16(f[0], f[1]); w.y = pk_bf16(f[2], f[3]); w.z = pk_bf16(f[4], f[5]); w.w = pk_bf16(f[6], f[7]); return w; }
; #define AT_LDV(buf, hs) do { const LAS unsigned char* vp_ = va + ((((hs) >> 1) >> 1) * 32 + 16 * (((hs) >> 1) & 1)) * AT_VROW + ((hs) & 1) * 128; _Pragma("unroll") for (int d_ = 0; d_ < 2; ++d_) { vf[buf][2 * d_] = vtr(vp_ + d_ * 64); vf[buf][2 * d_ + 1] = vtr(vp_ + 8 * AT_VROW + d_ * 64); } } while (0)
; __device__ __forceinline__ void attn_phase(LAS unsigned char* lds, const bf16* Q, const bf16* KV, const bf16* KPE, const float* rope, bf16* mix, int bid, int G, int tid) {
;     ...
;                 const float alpha = __builtin_amdgcn_exp2f(mrun - mnew); mrun = mnew;
;                 float rs = 0.f;
; #pragma unroll
;                 for (int e = 0; e < 16; ++e) { S0[e] = __builtin_amdgcn_exp2f(S0[e] - mnew); S1[e] = __builtin_amdgcn_exp2f(S1[e] - mnew); rs += S0[e] + S1[e]; }
;                 lrun = lrun * alpha + rs;
;                 if (__builtin_amdgcn_ballot_w64(alpha != 1.0f) != 0ull) {
; #pragma unroll
;                     for (int i = 0; i < 4; ++i)
; #pragma unroll
;                         for (int e = 0; e < 16; ++e) O[i][e] *= alpha; }
; #pragma unroll
;                 for (int hs = 0; hs < 8; ++hs) { const int st = hs >> 1;
;                     if (hs < 7) { AT_LDV((hs + 1) & 1, hs + 1); }
;                     __builtin_amdgcn_sched_barrier(0);
;                     float pf[8];
; #pragma unroll
;                     for (int e = 0; e < 8; ++e) pf[e] = (st >> 1) ? S1[8 * (st & 1) + e] : S0[8 * (st & 1) + e];
;                     const bf16x8 pb = __builtin_bit_cast(bf16x8, pack8(pf));
; #pragma unroll
;                     for (int d_ = 0; d_ < 2; ++d_) { const int dvt = (hs & 1) * 2 + d_; const s16x4 lo = vf[hs & 1][2 * d_], hi = vf[hs & 1][2 * d_ + 1];
;                         const bf16x8 A = (bf16x8){lo[0], lo[1], lo[2], lo[3], hi[0], hi[1], hi[2], hi[3]};
;                         __builtin_amdgcn_s_setprio(1); O[dvt] = __builtin_amdgcn_mfma_f32_32x32x16_bf16(A, pb, O[dvt], 0, 0, 0); __builtin_amdgcn_s_setprio(0); }
;                     __builtin_amdgcn_sched_barrier(0); }
.LBB0_258:
	v_sub_f32_e32 v80, v80, v209
	v_sub_f32_e32 v64, v64, v209
	v_exp_f32_e32 v80, v80
	v_exp_f32_e32 v210, v64
	v_sub_f32_e32 v81, v81, v209
	v_sub_f32_e32 v65, v65, v209
	v_exp_f32_e32 v81, v81
	v_exp_f32_e32 v211, v65
	v_add_f32_e32 v64, v80, v210
	v_add_f32_e32 v65, v81, v211
	v_add_f32_e32 v64, v65, v64
	v_sub_f32_e32 v65, v82, v209
	v_exp_f32_e32 v82, v65
	v_sub_f32_e32 v65, v66, v209
	v_exp_f32_e32 v212, v65
	s_nop 0
	v_add_f32_e32 v65, v82, v212
	v_add_f32_e32 v64, v65, v64
	v_sub_f32_e32 v65, v83, v209
	v_exp_f32_e32 v83, v65
	v_sub_f32_e32 v65, v67, v209
	v_exp_f32_e32 v213, v65
	s_nop 0
	v_add_f32_e32 v65, v83, v213
	v_add_f32_e32 v64, v65, v64
	v_sub_f32_e32 v65, v84, v209
	v_exp_f32_e32 v84, v65
	v_sub_f32_e32 v65, v68, v209
	v_exp_f32_e32 v214, v65
	s_nop 0
	v_add_f32_e32 v65, v84, v214
	v_add_f32_e32 v64, v65, v64
	v_sub_f32_e32 v65, v85, v209
	v_exp_f32_e32 v85, v65
	v_sub_f32_e32 v65, v69, v209
	v_exp_f32_e32 v215, v65
	s_nop 0
	v_add_f32_e32 v65, v85, v215
	v_add_f32_e32 v64, v65, v64
	v_sub_f32_e32 v65, v86, v209
	v_exp_f32_e32 v86, v65
	v_sub_f32_e32 v65, v70, v209
	v_exp_f32_e32 v228, v65
	s_nop 0
	v_add_f32_e32 v65, v86, v228
	v_add_f32_e32 v64, v65, v64
	v_sub_f32_e32 v65, v87, v209
	v_exp_f32_e32 v87, v65
	v_sub_f32_e32 v65, v71, v209
	v_exp_f32_e32 v229, v65
	s_nop 0
	v_add_f32_e32 v65, v87, v229
	v_add_f32_e32 v64, v65, v64
	v_sub_f32_e32 v65, v88, v209
	v_exp_f32_e32 v88, v65
	v_sub_f32_e32 v65, v72, v209
	v_exp_f32_e32 v230, v65
	s_nop 0
	v_add_f32_e32 v65, v88, v230
	v_add_f32_e32 v64, v65, v64
	v_sub_f32_e32 v65, v89, v209
	v_exp_f32_e32 v89, v65
	v_sub_f32_e32 v65, v73, v209
	v_exp_f32_e32 v231, v65
	s_nop 0
	v_add_f32_e32 v65, v89, v231
	v_add_f32_e32 v64, v65, v64
	v_sub_f32_e32 v65, v90, v209
	v_exp_f32_e32 v90, v65
	v_sub_f32_e32 v65, v74, v209
	v_exp_f32_e32 v232, v65
	s_nop 0
	v_add_f32_e32 v65, v90, v232
	v_add_f32_e32 v64, v65, v64
	v_sub_f32_e32 v65, v91, v209
	v_exp_f32_e32 v91, v65
	v_sub_f32_e32 v65, v75, v209
	v_exp_f32_e32 v233, v65
	s_nop 0
	v_add_f32_e32 v65, v91, v233
	v_add_f32_e32 v64, v65, v64
	v_sub_f32_e32 v65, v92, v209
	v_exp_f32_e32 v92, v65
	v_sub_f32_e32 v65, v76, v209
	v_exp_f32_e32 v234, v65
	s_nop 0
	v_add_f32_e32 v65, v92, v234
	v_add_f32_e32 v64, v65, v64
	v_sub_f32_e32 v65, v93, v209
	v_exp_f32_e32 v93, v65
	v_sub_f32_e32 v65, v77, v209
	v_exp_f32_e32 v235, v65
	s_nop 0
	v_add_f32_e32 v65, v93, v235
	v_add_f32_e32 v64, v65, v64
	v_sub_f32_e32 v65, v94, v209
	v_exp_f32_e32 v94, v65
	v_sub_f32_e32 v65, v78, v209
	v_exp_f32_e32 v236, v65
	s_nop 0
	v_add_f32_e32 v65, v94, v236
	v_add_f32_e32 v64, v65, v64
	v_sub_f32_e32 v65, v95, v209
	v_exp_f32_e32 v95, v65
	v_sub_f32_e32 v65, v79, v209
	v_exp_f32_e32 v237, v65
	s_nop 0
	v_add_f32_e32 v65, v95, v237
	v_add_f32_e32 v242, v65, v64
	ds_read_b64_tr_b16 v[64:65], v208 offset:25728
	ds_read_b64_tr_b16 v[66:67], v208 offset:28288
	ds_read_b64_tr_b16 v[68:69], v208 offset:25792
	ds_read_b64_tr_b16 v[70:71], v208 offset:28352
	v_fmac_f32_e32 v242, v207, v184
	v_cvt_pk_bf16_f32 v72, v80, v81
	v_cvt_pk_bf16_f32 v73, v82, v83
	v_cvt_pk_bf16_f32 v74, v84, v85
	v_cvt_pk_bf16_f32 v75, v86, v87
	s_setprio 1
	s_nop 0
	v_mfma_f32_32x32x16_bf16 v[48:63], v[170:173], v[72:75], v[48:63]
	s_setprio 0
	s_setprio 1
	v_mfma_f32_32x32x16_bf16 v[32:47], v[166:169], v[72:75], v[32:47]
	s_setprio 0
	ds_read_b64_tr_b16 v[76:77], v208 offset:30720
	ds_read_b64_tr_b16 v[78:79], v208 offset:33280
	ds_read_b64_tr_b16 v[80:81], v208 offset:30784
	ds_read_b64_tr_b16 v[82:83], v208 offset:33344
	s_setprio 1
	s_waitcnt lgkmcnt(0)
	v_mfma_f32_32x32x16_bf16 v[16:31], v[64:67], v[72:75], v[16:31]
	s_setprio 0
	s_setprio 1
	v_mfma_f32_32x32x16_bf16 v[0:15], v[68:71], v[72:75], v[0:15]
	s_setprio 0
	ds_read_b64_tr_b16 v[64:65], v208 offset:30848
	ds_read_b64_tr_b16 v[66:67], v208 offset:33408
	ds_read_b64_tr_b16 v[68:69], v208 offset:30912
	ds_read_b64_tr_b16 v[70:71], v208 offset:33472
	v_cvt_pk_bf16_f32 v72, v88, v89
	v_cvt_pk_bf16_f32 v73, v90, v91
	v_cvt_pk_bf16_f32 v74, v92, v93
	v_cvt_pk_bf16_f32 v75, v94, v95
	s_setprio 1
	s_nop 0
	v_mfma_f32_32x32x16_bf16 v[48:63], v[76:79], v[72:75], v[48:63]
	s_setprio 0
	s_setprio 1
	v_mfma_f32_32x32x16_bf16 v[32:47], v[80:83], v[72:75], v[32:47]
	s_setprio 0
	ds_read_b64_tr_b16 v[76:77], v208 offset:35840
	ds_read_b64_tr_b16 v[78:79], v208 offset:38400
	ds_read_b64_tr_b16 v[82:83], v208 offset:38464
	ds_read_b64_tr_b16 v[80:81], v208 offset:35904
	s_setprio 1
	s_waitcnt lgkmcnt(0)
	v_mfma_f32_32x32x16_bf16 v[16:31], v[64:67], v[72:75], v[16:31]
	s_setprio 0
	s_setprio 1
	v_mfma_f32_32x32x16_bf16 v[0:15], v[68:71], v[72:75], v[0:15]
	s_setprio 0
	ds_read_b64_tr_b16 v[64:65], v208 offset:35968
	ds_read_b64_tr_b16 v[66:67], v208 offset:38528
	ds_read_b64_tr_b16 v[70:71], v208 offset:38592
	ds_read_b64_tr_b16 v[68:69], v208 offset:36032
	v_cvt_pk_bf16_f32 v72, v210, v211
	v_cvt_pk_bf16_f32 v73, v212, v213
	v_cvt_pk_bf16_f32 v74, v214, v215
	v_cvt_pk_bf16_f32 v75, v228, v229
	s_setprio 1
	s_nop 0
	v_mfma_f32_32x32x16_bf16 v[48:63], v[76:79], v[72:75], v[48:63]
	s_setprio 0
	s_setprio 1
	v_mfma_f32_32x32x16_bf16 v[32:47], v[80:83], v[72:75], v[32:47]
	s_setprio 0
	ds_read_b64_tr_b16 v[76:77], v208 offset:40960
	ds_read_b64_tr_b16 v[78:79], v208 offset:43520
	ds_read_b64_tr_b16 v[82:83], v208 offset:43584
	ds_read_b64_tr_b16 v[80:81], v208 offset:41024
	s_setprio 1
	s_waitcnt lgkmcnt(0)
	v_mfma_f32_32x32x16_bf16 v[16:31], v[64:67], v[72:75], v[16:31]
	s_setprio 0
	s_setprio 1
	v_mfma_f32_32x32x16_bf16 v[0:15], v[68:71], v[72:75], v[0:15]
	s_setprio 0
	ds_read_b64_tr_b16 v[64:65], v208 offset:41088
	ds_read_b64_tr_b16 v[66:67], v208 offset:43648
	ds_read_b64_tr_b16 v[70:71], v208 offset:43712
	ds_read_b64_tr_b16 v[68:69], v208 offset:41152
	v_cvt_pk_bf16_f32 v72, v230, v231
	v_cvt_pk_bf16_f32 v73, v232, v233
	v_cvt_pk_bf16_f32 v74, v234, v235
	v_cvt_pk_bf16_f32 v75, v236, v237
	s_setprio 1
	s_nop 0
	v_mfma_f32_32x32x16_bf16 v[48:63], v[76:79], v[72:75], v[48:63]
	s_setprio 0
	s_setprio 1
	v_mfma_f32_32x32x16_bf16 v[32:47], v[80:83], v[72:75], v[32:47]
	s_setprio 0
	s_setprio 1
	s_waitcnt lgkmcnt(0)
	v_mfma_f32_32x32x16_bf16 v[16:31], v[64:67], v[72:75], v[16:31]
	s_setprio 0
	s_setprio 1
	v_mfma_f32_32x32x16_bf16 v[0:15], v[68:71], v[72:75], v[0:15]
	s_setprio 0
	v_mov_b32_e32 v207, v242
	s_andn2_b64 vcc, exec, s[34:35]
	s_cbranch_vccz .LBB0_260
	s_branch .LBB0_261
